# scan loader weight copies pack bf16 pairs with v_cvt_pk_bf16_f32 instead of the integer RNE sequence
# speedup vs baseline: 1.0165x; 1.0046x over previous
.LBB0_575:
	s_or_b64 exec, exec, s[10:11]
	s_mul_i32 s6, s55, 0x2100
	s_add_i32 s6, s6, 0
	s_add_i32 s6, s6, 0x18200
	v_lshlrev_b32_e32 v136, 2, v110
	v_add3_u32 v223, s6, v136, v198
	v_lshlrev_b32_e32 v1, 2, v192
	v_add3_u32 v220, s6, v193, v1
	s_andn2_b64 vcc, exec, s[4:5]
	v_add_u32_e32 v228, 0x400, v223
	v_add_u32_e32 v227, 0x800, v223
	v_add_u32_e32 v226, 0xc00, v223
	v_add_u32_e32 v225, 0x1000, v223
	v_add_u32_e32 v224, 0x1400, v223
	v_add_u32_e32 v222, 0x1800, v223
	v_add_u32_e32 v221, 0x1c00, v223
	v_lshlrev_b32_e32 v2, 1, v114
	s_cbranch_vccnz .LBB0_577
	v_ashrrev_i32_e32 v1, 31, v218
	v_lshrrev_b32_e32 v1, 27, v1
	v_add_u32_e32 v1, v218, v1
	v_ashrrev_i32_e32 v1, 5, v1
	v_sub_u32_e32 v3, 0, v1
	v_max_i32_e32 v3, v1, v3
	v_cvt_f32_u32_e32 v72, v3
	v_sub_u32_e32 v75, 0, v3
	v_sub_u32_e32 v73, 0, v217
	v_max_i32_e32 v73, v217, v73
	v_rcp_iflag_f32_e32 v72, v72
	v_xor_b32_e32 v74, v217, v1
	s_waitcnt vmcnt(38)
	ds_write2_b32 v223, v4, v5 offset1:66
	s_waitcnt vmcnt(36)
	ds_write2_b32 v223, v6, v7 offset0:132 offset1:198
	s_waitcnt vmcnt(34)
	ds_write2_b32 v228, v8, v9 offset0:8 offset1:74
	s_waitcnt vmcnt(32)
	ds_write2_b32 v228, v10, v11 offset0:140 offset1:206
	s_waitcnt vmcnt(30)
	ds_write2_b32 v227, v12, v13 offset0:16 offset1:82
	s_waitcnt vmcnt(28)
	ds_write2_b32 v227, v14, v15 offset0:148 offset1:214
	s_waitcnt vmcnt(26)
	ds_write2_b32 v226, v16, v17 offset0:24 offset1:90
	s_waitcnt vmcnt(24)
	ds_write2_b32 v226, v18, v19 offset0:156 offset1:222
	s_waitcnt vmcnt(22)
	ds_write2_b32 v225, v20, v21 offset0:32 offset1:98
	s_waitcnt vmcnt(20)
	ds_write2_b32 v225, v22, v23 offset0:164 offset1:230
	s_waitcnt vmcnt(18)
	ds_write2_b32 v224, v24, v25 offset0:40 offset1:106
	s_waitcnt vmcnt(16)
	ds_write2_b32 v224, v26, v27 offset0:172 offset1:238
	s_waitcnt vmcnt(14)
	ds_write2_b32 v222, v28, v29 offset0:48 offset1:114
	s_waitcnt vmcnt(12)
	ds_write2_b32 v222, v30, v31 offset0:180 offset1:246
	s_waitcnt vmcnt(10)
	ds_write2_b32 v221, v32, v33 offset0:56 offset1:122
	s_waitcnt vmcnt(8)
	ds_write2_b32 v221, v34, v35 offset0:188 offset1:254
	v_ashrrev_i32_e32 v74, 31, v74
	v_mul_f32_e32 v72, 0x4f7ffffe, v72
	v_cvt_u32_f32_e32 v72, v72
	s_waitcnt lgkmcnt(0)
	ds_read2_b32 v[80:81], v220 offset0:33 offset1:41
	ds_read2_b32 v[82:83], v220 offset0:66 offset1:74
	v_mul_lo_u32 v75, v75, v72
	v_mul_hi_u32 v75, v72, v75
	v_add_u32_e32 v72, v72, v75
	v_mul_hi_u32 v72, v73, v72
	v_mul_lo_u32 v75, v72, v3
	v_sub_u32_e32 v73, v73, v75
	v_add_u32_e32 v76, 1, v72
	v_cmp_ge_u32_e32 vcc, v73, v3
	v_sub_u32_e32 v75, v73, v3
	ds_read2_b32 v[84:85], v220 offset0:99 offset1:107
	v_cndmask_b32_e32 v72, v72, v76, vcc
	v_cndmask_b32_e32 v73, v73, v75, vcc
	v_add_u32_e32 v75, 1, v72
	v_cmp_ge_u32_e32 vcc, v73, v3
	ds_read2_b32 v[76:77], v220 offset1:8
	ds_read2_b32 v[86:87], v220 offset0:132 offset1:140
	v_cndmask_b32_e32 v3, v72, v75, vcc
	v_xor_b32_e32 v3, v3, v74
	v_sub_u32_e32 v3, v3, v74
	v_lshlrev_b32_e32 v72, 6, v3
	v_ashrrev_i32_e32 v73, 31, v72
	v_mul_lo_u32 v1, v3, v1
	v_lshl_add_u64 v[72:73], v[72:73], 1, v[132:133]
	v_mov_b32_e32 v3, v0
	v_lshl_add_u64 v[78:79], v[72:73], 0, v[2:3]
	s_waitcnt lgkmcnt(1)
	ds_read2_b32 v[88:89], v220 offset0:165 offset1:173
	v_cvt_pk_bf16_f32 v72, v76, v80
	ds_read2_b32 v[90:91], v220 offset0:198 offset1:206
	ds_read2_b32 v[134:135], v220 offset0:231 offset1:239
	v_cvt_pk_bf16_f32 v73, v82, v84
	s_waitcnt lgkmcnt(3)
	s_waitcnt lgkmcnt(2)
	v_cvt_pk_bf16_f32 v74, v86, v88
	s_waitcnt lgkmcnt(1)
	v_sub_u32_e32 v1, v217, v1
	s_waitcnt lgkmcnt(0)
	v_lshlrev_b32_e32 v1, 5, v1
	v_cvt_pk_bf16_f32 v75, v90, v134
	v_or_b32_e32 v3, v1, v192
	v_mad_i64_i32 v[138:139], s[4:5], v3, v219, 0
	v_lshl_add_u64 v[138:139], v[138:139], 1, v[78:79]
	global_store_dwordx4 v[138:139], v[72:75], off
	s_nop 1
	v_cvt_pk_bf16_f32 v72, v77, v81
	v_cvt_pk_bf16_f32 v73, v83, v85
	v_cvt_pk_bf16_f32 v74, v87, v89
	v_cvt_pk_bf16_f32 v75, v91, v135
	v_or_b32_e32 v3, v1, v199
	v_mad_i64_i32 v[80:81], s[4:5], v3, v219, 0
	ds_read2_b32 v[76:77], v220 offset0:16 offset1:24
	v_lshl_add_u64 v[80:81], v[80:81], 1, v[78:79]
	global_store_dwordx4 v[80:81], v[72:75], off
	ds_read2_b32 v[80:81], v220 offset0:49 offset1:57
	ds_read2_b32 v[82:83], v220 offset0:82 offset1:90
	ds_read2_b32 v[84:85], v220 offset0:115 offset1:123
	s_waitcnt lgkmcnt(3)
	s_waitcnt lgkmcnt(2)
	ds_read2_b32 v[86:87], v220 offset0:148 offset1:156
	ds_read2_b32 v[88:89], v220 offset0:181 offset1:189
	v_cvt_pk_bf16_f32 v72, v76, v80
	s_waitcnt lgkmcnt(3)
	s_waitcnt lgkmcnt(2)
	ds_read2_b32 v[90:91], v220 offset0:214 offset1:222
	ds_read2_b32 v[134:135], v220 offset0:247 offset1:255
	v_cvt_pk_bf16_f32 v73, v82, v84
	s_waitcnt lgkmcnt(3)
	s_waitcnt lgkmcnt(2)
	v_cvt_pk_bf16_f32 v74, v86, v88
	s_waitcnt lgkmcnt(1)
	s_waitcnt lgkmcnt(0)
	v_cvt_pk_bf16_f32 v75, v90, v134
	v_or_b32_e32 v3, v1, v200
	v_mad_i64_i32 v[138:139], s[4:5], v3, v219, 0
	v_lshl_add_u64 v[138:139], v[138:139], 1, v[78:79]
	global_store_dwordx4 v[138:139], v[72:75], off
	s_nop 1
	v_cvt_pk_bf16_f32 v72, v77, v81
	v_cvt_pk_bf16_f32 v73, v83, v85
	v_cvt_pk_bf16_f32 v74, v87, v89
	v_or_b32_e32 v1, v1, v201
	v_mad_i64_i32 v[76:77], s[4:5], v1, v219, 0
	v_cvt_pk_bf16_f32 v75, v91, v135
	v_lshl_add_u64 v[76:77], v[76:77], 1, v[78:79]
	global_store_dwordx4 v[76:77], v[72:75], off
	s_waitcnt lgkmcnt(0)

.LBB0_621:
	s_and_b32 s6, s56, 0x400
	v_lshl_add_u32 v1, s6, 2, v191
	ds_read_b128 v[72:75], v1
	v_add_u32_e32 v76, s38, v164
	v_ashrrev_i32_e32 v77, 31, v76
	v_lshlrev_b64 v[76:77], 13, v[76:77]
	v_lshl_add_u64 v[76:77], v[138:139], 0, v[76:77]
	s_andn2_b64 vcc, exec, s[8:9]
	s_waitcnt lgkmcnt(0)
	global_store_dwordx4 v[76:77], v[72:75], off
	s_cbranch_vccnz .LBB0_623
	v_ashrrev_i32_e32 v1, 31, v218
	v_lshrrev_b32_e32 v1, 27, v1
	v_add_u32_e32 v1, v218, v1
	v_ashrrev_i32_e32 v1, 5, v1
	v_sub_u32_e32 v3, 0, v1
	v_max_i32_e32 v3, v1, v3
	v_cvt_f32_u32_e32 v72, v3
	v_sub_u32_e32 v75, 0, v3
	v_sub_u32_e32 v73, 0, v217
	v_max_i32_e32 v73, v217, v73
	v_rcp_iflag_f32_e32 v72, v72
	v_xor_b32_e32 v74, v217, v1
	s_waitcnt vmcnt(31)
	ds_write2_b32 v223, v4, v5 offset1:66
	s_waitcnt vmcnt(29)
	ds_write2_b32 v223, v6, v7 offset0:132 offset1:198
	s_waitcnt vmcnt(27)
	ds_write2_b32 v228, v8, v9 offset0:8 offset1:74
	s_waitcnt vmcnt(25)
	ds_write2_b32 v228, v10, v11 offset0:140 offset1:206
	s_waitcnt vmcnt(23)
	ds_write2_b32 v227, v12, v13 offset0:16 offset1:82
	s_waitcnt vmcnt(21)
	ds_write2_b32 v227, v14, v15 offset0:148 offset1:214
	s_waitcnt vmcnt(19)
	ds_write2_b32 v226, v16, v17 offset0:24 offset1:90
	s_waitcnt vmcnt(17)
	ds_write2_b32 v226, v18, v19 offset0:156 offset1:222
	s_waitcnt vmcnt(15)
	ds_write2_b32 v225, v20, v21 offset0:32 offset1:98
	s_waitcnt vmcnt(13)
	ds_write2_b32 v225, v22, v23 offset0:164 offset1:230
	s_waitcnt vmcnt(11)
	ds_write2_b32 v224, v24, v25 offset0:40 offset1:106
	s_waitcnt vmcnt(9)
	ds_write2_b32 v224, v26, v27 offset0:172 offset1:238
	s_waitcnt vmcnt(7)
	ds_write2_b32 v222, v28, v29 offset0:48 offset1:114
	s_waitcnt vmcnt(5)
	ds_write2_b32 v222, v30, v31 offset0:180 offset1:246
	s_waitcnt vmcnt(3)
	ds_write2_b32 v221, v32, v33 offset0:56 offset1:122
	s_waitcnt vmcnt(1)
	ds_write2_b32 v221, v34, v35 offset0:188 offset1:254
	v_ashrrev_i32_e32 v74, 31, v74
	v_mul_f32_e32 v72, 0x4f7ffffe, v72
	v_cvt_u32_f32_e32 v72, v72
	s_waitcnt lgkmcnt(0)
	ds_read2_b32 v[80:81], v220 offset0:33 offset1:41
	ds_read2_b32 v[82:83], v220 offset0:66 offset1:74
	v_mul_lo_u32 v75, v75, v72
	v_mul_hi_u32 v75, v72, v75
	v_add_u32_e32 v72, v72, v75
	v_mul_hi_u32 v72, v73, v72
	v_mul_lo_u32 v75, v72, v3
	v_sub_u32_e32 v73, v73, v75
	v_add_u32_e32 v76, 1, v72
	v_cmp_ge_u32_e32 vcc, v73, v3
	v_sub_u32_e32 v75, v73, v3
	ds_read2_b32 v[84:85], v220 offset0:99 offset1:107
	v_cndmask_b32_e32 v72, v72, v76, vcc
	v_cndmask_b32_e32 v73, v73, v75, vcc
	v_add_u32_e32 v75, 1, v72
	v_cmp_ge_u32_e32 vcc, v73, v3
	ds_read2_b32 v[76:77], v220 offset1:8
	ds_read2_b32 v[86:87], v220 offset0:132 offset1:140
	v_cndmask_b32_e32 v3, v72, v75, vcc
	v_xor_b32_e32 v3, v3, v74
	v_sub_u32_e32 v3, v3, v74
	v_lshlrev_b32_e32 v72, 6, v3
	v_ashrrev_i32_e32 v73, 31, v72
	v_mul_lo_u32 v1, v3, v1
	v_lshl_add_u64 v[72:73], v[72:73], 1, v[132:133]
	v_mov_b32_e32 v3, v0
	v_lshl_add_u64 v[78:79], v[72:73], 0, v[2:3]
	s_waitcnt lgkmcnt(1)
	ds_read2_b32 v[88:89], v220 offset0:165 offset1:173
	v_cvt_pk_bf16_f32 v72, v76, v80
	ds_read2_b32 v[90:91], v220 offset0:198 offset1:206
	ds_read2_b32 v[230:231], v220 offset0:231 offset1:239
	v_cvt_pk_bf16_f32 v73, v82, v84
	s_waitcnt lgkmcnt(3)
	s_waitcnt lgkmcnt(2)
	v_cvt_pk_bf16_f32 v74, v86, v88
	s_waitcnt lgkmcnt(1)
	v_sub_u32_e32 v1, v217, v1
	s_waitcnt lgkmcnt(0)
	v_lshlrev_b32_e32 v1, 5, v1
	v_cvt_pk_bf16_f32 v75, v90, v230
	v_or_b32_e32 v3, v1, v192
	v_mad_i64_i32 v[232:233], s[6:7], v3, v219, 0
	v_lshl_add_u64 v[232:233], v[232:233], 1, v[78:79]
	global_store_dwordx4 v[232:233], v[72:75], off
	s_nop 1
	v_cvt_pk_bf16_f32 v72, v77, v81
	v_cvt_pk_bf16_f32 v73, v83, v85
	v_cvt_pk_bf16_f32 v74, v87, v89
	v_cvt_pk_bf16_f32 v75, v91, v231
	v_or_b32_e32 v3, v1, v199
	v_mad_i64_i32 v[80:81], s[6:7], v3, v219, 0
	ds_read2_b32 v[76:77], v220 offset0:16 offset1:24
	v_lshl_add_u64 v[80:81], v[80:81], 1, v[78:79]
	global_store_dwordx4 v[80:81], v[72:75], off
	ds_read2_b32 v[80:81], v220 offset0:49 offset1:57
	ds_read2_b32 v[82:83], v220 offset0:82 offset1:90
	ds_read2_b32 v[84:85], v220 offset0:115 offset1:123
	s_waitcnt lgkmcnt(3)
	s_waitcnt lgkmcnt(2)
	ds_read2_b32 v[86:87], v220 offset0:148 offset1:156
	ds_read2_b32 v[88:89], v220 offset0:181 offset1:189
	v_cvt_pk_bf16_f32 v72, v76, v80
	s_waitcnt lgkmcnt(3)
	s_waitcnt lgkmcnt(2)
	ds_read2_b32 v[90:91], v220 offset0:214 offset1:222
	ds_read2_b32 v[230:231], v220 offset0:247 offset1:255
	v_cvt_pk_bf16_f32 v73, v82, v84
	s_waitcnt lgkmcnt(3)
	s_waitcnt lgkmcnt(2)
	v_cvt_pk_bf16_f32 v74, v86, v88
	s_waitcnt lgkmcnt(1)
	s_waitcnt lgkmcnt(0)
	v_cvt_pk_bf16_f32 v75, v90, v230
	v_or_b32_e32 v3, v1, v200
	v_mad_i64_i32 v[232:233], s[6:7], v3, v219, 0
	v_lshl_add_u64 v[232:233], v[232:233], 1, v[78:79]
	global_store_dwordx4 v[232:233], v[72:75], off
	s_nop 1
	v_cvt_pk_bf16_f32 v72, v77, v81
	v_cvt_pk_bf16_f32 v73, v83, v85
	v_cvt_pk_bf16_f32 v74, v87, v89
	v_or_b32_e32 v1, v1, v201
	v_mad_i64_i32 v[76:77], s[6:7], v1, v219, 0
	v_cvt_pk_bf16_f32 v75, v91, v231
	v_lshl_add_u64 v[76:77], v[76:77], 1, v[78:79]
	global_store_dwordx4 v[76:77], v[72:75], off
	s_waitcnt lgkmcnt(0)

.LBB0_645:
	v_add_u32_e32 v1, s86, v190
	ds_read_b128 v[36:39], v191
	v_add_u32_e32 v40, 0x7c0, v1
	v_ashrrev_i32_e32 v41, 31, v40
	s_xor_b64 s[8:9], s[8:9], -1
	v_lshlrev_b64 v[40:41], 13, v[40:41]
	v_lshl_add_u64 v[40:41], v[138:139], 0, v[40:41]
	s_andn2_b64 vcc, exec, s[8:9]
	s_waitcnt lgkmcnt(0)
	global_store_dwordx4 v[40:41], v[36:39], off
	s_cbranch_vccnz .LBB0_647
	v_ashrrev_i32_e32 v1, 31, v218
	v_lshrrev_b32_e32 v1, 27, v1
	v_add_u32_e32 v1, v218, v1
	v_ashrrev_i32_e32 v1, 5, v1
	v_sub_u32_e32 v3, 0, v1
	v_max_i32_e32 v3, v1, v3
	v_cvt_f32_u32_e32 v36, v3
	v_sub_u32_e32 v39, 0, v3
	v_sub_u32_e32 v37, 0, v217
	v_max_i32_e32 v37, v217, v37
	v_rcp_iflag_f32_e32 v36, v36
	v_xor_b32_e32 v38, v217, v1
	s_waitcnt vmcnt(8)
	ds_write2_b32 v223, v4, v5 offset1:66
	ds_write2_b32 v223, v6, v7 offset0:132 offset1:198
	s_waitcnt vmcnt(7)
	ds_write2_b32 v228, v8, v9 offset0:8 offset1:74
	ds_write2_b32 v228, v10, v11 offset0:140 offset1:206
	s_waitcnt vmcnt(6)
	ds_write2_b32 v227, v12, v13 offset0:16 offset1:82
	ds_write2_b32 v227, v14, v15 offset0:148 offset1:214
	s_waitcnt vmcnt(5)
	ds_write2_b32 v226, v16, v17 offset0:24 offset1:90
	ds_write2_b32 v226, v18, v19 offset0:156 offset1:222
	s_waitcnt vmcnt(4)
	ds_write2_b32 v225, v20, v21 offset0:32 offset1:98
	ds_write2_b32 v225, v22, v23 offset0:164 offset1:230
	s_waitcnt vmcnt(3)
	ds_write2_b32 v224, v24, v25 offset0:40 offset1:106
	ds_write2_b32 v224, v26, v27 offset0:172 offset1:238
	s_waitcnt vmcnt(2)
	ds_write2_b32 v222, v28, v29 offset0:48 offset1:114
	ds_write2_b32 v222, v30, v31 offset0:180 offset1:246
	s_waitcnt vmcnt(1)
	ds_write2_b32 v221, v32, v33 offset0:56 offset1:122
	ds_write2_b32 v221, v34, v35 offset0:188 offset1:254
	v_ashrrev_i32_e32 v38, 31, v38
	v_mul_f32_e32 v36, 0x4f7ffffe, v36
	v_cvt_u32_f32_e32 v36, v36
	s_waitcnt lgkmcnt(0)
	ds_read2_b32 v[42:43], v220 offset0:33 offset1:41
	ds_read2_b32 v[44:45], v220 offset0:66 offset1:74
	v_mul_lo_u32 v39, v39, v36
	v_mul_hi_u32 v39, v36, v39
	v_add_u32_e32 v36, v36, v39
	v_mul_hi_u32 v36, v37, v36
	v_mul_lo_u32 v39, v36, v3
	v_sub_u32_e32 v37, v37, v39
	v_add_u32_e32 v40, 1, v36
	v_cmp_ge_u32_e32 vcc, v37, v3
	v_sub_u32_e32 v39, v37, v3
	ds_read2_b32 v[46:47], v220 offset0:99 offset1:107
	v_cndmask_b32_e32 v36, v36, v40, vcc
	v_cndmask_b32_e32 v37, v37, v39, vcc
	v_add_u32_e32 v39, 1, v36
	v_cmp_ge_u32_e32 vcc, v37, v3
	ds_read2_b32 v[40:41], v220 offset1:8
	ds_read2_b32 v[64:65], v220 offset0:132 offset1:140
	v_cndmask_b32_e32 v3, v36, v39, vcc
	v_xor_b32_e32 v3, v3, v38
	v_sub_u32_e32 v3, v3, v38
	v_lshlrev_b32_e32 v36, 6, v3
	v_ashrrev_i32_e32 v37, 31, v36
	v_mul_lo_u32 v1, v3, v1
	v_lshl_add_u64 v[36:37], v[36:37], 1, v[132:133]
	v_mov_b32_e32 v3, v0
	v_lshl_add_u64 v[2:3], v[36:37], 0, v[2:3]
	s_waitcnt lgkmcnt(1)
	ds_read2_b32 v[66:67], v220 offset0:165 offset1:173
	v_cvt_pk_bf16_f32 v36, v40, v42
	ds_read2_b32 v[68:69], v220 offset0:198 offset1:206
	ds_read2_b32 v[70:71], v220 offset0:231 offset1:239
	v_cvt_pk_bf16_f32 v37, v44, v46
	s_waitcnt lgkmcnt(3)
	s_waitcnt lgkmcnt(2)
	v_cvt_pk_bf16_f32 v38, v64, v66
	s_waitcnt lgkmcnt(1)
	v_sub_u32_e32 v1, v217, v1
	s_waitcnt lgkmcnt(0)
	v_lshlrev_b32_e32 v1, 5, v1
	v_cvt_pk_bf16_f32 v39, v68, v70
	v_or_b32_e32 v40, v1, v192
	v_mad_i64_i32 v[72:73], s[6:7], v40, v219, 0
	v_lshl_add_u64 v[72:73], v[72:73], 1, v[2:3]
	global_store_dwordx4 v[72:73], v[36:39], off
	s_nop 1
	v_or_b32_e32 v42, v1, v199
	v_cvt_pk_bf16_f32 v36, v41, v43
	v_cvt_pk_bf16_f32 v37, v45, v47
	v_cvt_pk_bf16_f32 v38, v65, v67
	v_mad_i64_i32 v[42:43], s[6:7], v42, v219, 0
	v_cvt_pk_bf16_f32 v39, v69, v71
	ds_read2_b32 v[40:41], v220 offset0:16 offset1:24
	v_lshl_add_u64 v[42:43], v[42:43], 1, v[2:3]
	global_store_dwordx4 v[42:43], v[36:39], off
	ds_read2_b32 v[42:43], v220 offset0:49 offset1:57
	ds_read2_b32 v[44:45], v220 offset0:82 offset1:90
	ds_read2_b32 v[46:47], v220 offset0:115 offset1:123
	s_waitcnt lgkmcnt(3)
	s_waitcnt lgkmcnt(2)
	ds_read2_b32 v[64:65], v220 offset0:148 offset1:156
	ds_read2_b32 v[66:67], v220 offset0:181 offset1:189
	v_cvt_pk_bf16_f32 v36, v40, v42
	s_waitcnt lgkmcnt(3)
	s_waitcnt lgkmcnt(2)
	ds_read2_b32 v[68:69], v220 offset0:214 offset1:222
	ds_read2_b32 v[70:71], v220 offset0:247 offset1:255
	v_cvt_pk_bf16_f32 v37, v44, v46
	s_waitcnt lgkmcnt(3)
	s_waitcnt lgkmcnt(2)
	v_cvt_pk_bf16_f32 v38, v64, v66
	s_waitcnt lgkmcnt(1)
	s_waitcnt lgkmcnt(0)
	v_cvt_pk_bf16_f32 v39, v68, v70
	v_or_b32_e32 v40, v1, v200
	v_mad_i64_i32 v[72:73], s[6:7], v40, v219, 0
	v_lshl_add_u64 v[72:73], v[72:73], 1, v[2:3]
	global_store_dwordx4 v[72:73], v[36:39], off
	s_nop 1
	v_cvt_pk_bf16_f32 v36, v41, v43
	v_cvt_pk_bf16_f32 v37, v45, v47
	v_cvt_pk_bf16_f32 v38, v65, v67
	v_or_b32_e32 v1, v1, v201
	v_cvt_pk_bf16_f32 v39, v69, v71
	v_mad_i64_i32 v[40:41], s[6:7], v1, v219, 0
	v_lshl_add_u64 v[2:3], v[40:41], 1, v[2:3]
	global_store_dwordx4 v[2:3], v[36:39], off
	s_waitcnt lgkmcnt(0)
